# HGRN2 mixer part 2: removed the vmcnt(0) that only drained the previous chunk's output stores
# speedup vs baseline: 1.0045x; 1.0045x over previous
; #define LAS __attribute__((address_space(3)))
; __device__ __forceinline__ unsigned cvt_pk_bf16(float lo, float hi) { unsigned r; asm("v_cvt_pk_bf16_f32 %0, %1, %2" : "=v"(r) : "v"(lo), "v"(hi)); return r; }
; __device__ __forceinline__ float bf_lo(unsigned u) { return __uint_as_float(u << 16); }
; __device__ __forceinline__ float bf_hi(unsigned u) { return __uint_as_float(u & 0xffff0000u); }
; __device__ __forceinline__ float rcp_(float x) { return __builtin_amdgcn_rcpf(x); }
; __device__ __forceinline__ float exp2_(float x) { return __builtin_amdgcn_exp2f(x); }
; template <int DK, bool IS_A, int NDV>
; __device__ __forceinline__ void mix_stream(const Params& p, LAS unsigned char* lds, int l, int rs, int T, int h, int dir, int dvh) {
;     ...
;                 float pre0 = 0.f, pre1 = 0.f, ref0 = 0.f, ref1 = 0.f, tot0 = 0.f, tot1 = 0.f;
; #pragma unroll
;                 for (int s8 = 0; s8 < 8; ++s8) { const f32x2 v = *(const LAS f32x2*)(seg + s8 * DK + 2 * cp);
;                     if (s8 < sg) { pre0 += v.x; pre1 += v.y; } if (s8 < 4) { ref0 += v.x; ref1 += v.y; } tot0 += v.x; tot1 += v.y; }
;                 f32x2 E = (f32x2){exp2_(fminf(fmaxf(pre0 - ref0, -115.f), 115.f)), exp2_(fminf(fmaxf(pre1 - ref1, -115.f), 115.f))};
; #pragma unroll
;                 for (int ip = 0; ip < 4; ++ip) { unsigned kp[2];
; #pragma unroll
;                     for (int e = 0; e < 2; ++e) { const int i = 2 * ip + e;
;                         const f32x2 f = (f32x2){exp2_(bf_lo(rf[par][i])), exp2_(bf_hi(rf[par][i]))};
;                         E = __builtin_elementwise_max(E * f, (f32x2){1e-35f, 1e-35f});
;                         const f32x2 r = (f32x2){rcp_(E.x), rcp_(E.y)};
;                         const f32x2 k = r - f * r;
;                         const f32x2 qv = (f32x2){bf_lo(rq[par][i]), bf_hi(rq[par][i])} * E;
;                         const int t = sg * 8 + i;
;                         const int cb4 = (4 * cp) ^ ((i >= 4 ? 16 : 0) ^ sgx);
;                         *(LAS unsigned*)(Qs + t * QP + cb4) = cvt_pk_bf16(qv.x, qv.y);
;                         kp[e] = cvt_pk_bf16(k.x, k.y);
;                         *(LAS unsigned*)(Ks + t * QP + cb4) = kp[e]; }
.LBB0_175:
	ds_read2st64_b64 v[0:3], v108 offset1:1
	v_exp_f32_e32 v104, v104
	v_exp_f32_e32 v105, v105
	v_exp_f32_e32 v102, v102
	v_exp_f32_e32 v103, v103
	s_waitcnt lgkmcnt(0)
	v_add_f32_e32 v0, 0, v0
	v_add_f32_e32 v1, 0, v1
	v_cndmask_b32_e64 v4, 0, v1, s[58:59]
	v_cndmask_b32_e64 v5, 0, v0, s[58:59]
	v_add_f32_e32 v6, v2, v5
	v_add_f32_e32 v7, v3, v4
	v_cndmask_b32_e64 v4, v4, v7, s[60:61]
	v_cndmask_b32_e64 v5, v5, v6, s[60:61]
	v_add_f32_e32 v6, v0, v2
	v_add_f32_e32 v7, v1, v3
	ds_read2st64_b64 v[0:3], v108 offset0:2 offset1:3
	v_exp_f32_e32 v100, v100
	v_exp_f32_e32 v101, v101
	v_exp_f32_e32 v98, v98
	v_exp_f32_e32 v99, v99
	s_waitcnt lgkmcnt(0)
	v_add_f32_e32 v166, v0, v5
	v_add_f32_e32 v167, v1, v4
	v_cndmask_b32_e64 v4, v4, v167, s[62:63]
	v_cndmask_b32_e64 v5, v5, v166, s[62:63]
	v_add_f32_e32 v0, v6, v0
	v_add_f32_e32 v1, v7, v1
	v_add_f32_e32 v6, v2, v5
	v_add_f32_e32 v7, v3, v4
	v_add_f32_e32 v167, v0, v2
	v_add_f32_e32 v166, v1, v3
	ds_read2st64_b64 v[0:3], v108 offset0:4 offset1:5
	v_cndmask_b32_e64 v4, v4, v7, s[64:65]
	v_cndmask_b32_e64 v5, v5, v6, s[64:65]
	v_exp_f32_e32 v96, v96
	v_exp_f32_e32 v97, v97
	s_waitcnt lgkmcnt(0)
	v_add_f32_e32 v6, v0, v5
	v_add_f32_e32 v7, v1, v4
	v_cndmask_b32_e64 v4, v4, v7, s[66:67]
	v_cndmask_b32_e64 v5, v5, v6, s[66:67]
	v_add_f32_e32 v6, v2, v5
	v_add_f32_e32 v7, v3, v4
	v_cndmask_b32_e64 v168, v4, v7, s[68:69]
	v_cndmask_b32_e64 v169, v5, v6, s[68:69]
	ds_read2st64_b64 v[4:7], v108 offset0:6 offset1:7
	v_add_u32_e32 v172, s9, v112
	v_exp_f32_e32 v94, v94
	v_exp_f32_e32 v95, v95
	v_exp_f32_e32 v92, v92
	s_waitcnt lgkmcnt(0)
	v_add_f32_e32 v170, v4, v169
	v_add_f32_e32 v171, v5, v168
	v_cndmask_b32_e64 v168, v168, v171, s[70:71]
	v_cndmask_b32_e64 v169, v169, v170, s[70:71]
	v_add_f32_e32 v170, v6, v169
	v_add_f32_e32 v171, v7, v168
	v_cndmask_b32_e64 v171, v168, v171, s[72:73]
	v_cndmask_b32_e64 v168, v169, v170, s[72:73]
	v_sub_f32_e32 v168, v168, v167
	v_sub_f32_e32 v169, v171, v166
	v_med3_f32 v168, v168, s2, v240
	v_med3_f32 v169, v169, s2, v240
	v_exp_f32_e32 v168, v168
	v_exp_f32_e32 v169, v169
	v_exp_f32_e32 v93, v93
	v_exp_f32_e32 v90, v90
	v_exp_f32_e32 v91, v91
	v_pk_mul_f32 v[168:169], v[104:105], v[168:169]
	s_andn2_b64 vcc, exec, s[0:1]
	v_max_f32_e32 v169, 0x554ad2e, v169
	v_max_f32_e32 v168, 0x554ad2e, v168
	v_rcp_f32_e32 v170, v168
	v_rcp_f32_e32 v171, v169
	s_nop 0
	v_pk_fma_f32 v[104:105], v[104:105], v[170:171], v[170:171] neg_lo:[1,0,0] neg_hi:[1,0,0]
	v_lshlrev_b32_e32 v170, 16, v122
	v_and_b32_e32 v171, 0xffff0000, v122
	v_pk_mul_f32 v[170:171], v[168:169], v[170:171]
	v_pk_mul_f32 v[168:169], v[102:103], v[168:169]
	v_cvt_pk_bf16_f32 v170, v170, v171
	v_add_u32_e32 v171, s8, v112
	v_max_f32_e32 v169, 0x554ad2e, v169
	v_max_f32_e32 v168, 0x554ad2e, v168
	v_cvt_pk_bf16_f32 v104, v104, v105
	ds_write2st64_b32 v171, v170, v104 offset1:68
	v_rcp_f32_e32 v170, v168
	v_rcp_f32_e32 v171, v169
	s_nop 0
	v_pk_fma_f32 v[102:103], v[102:103], v[170:171], v[170:171] neg_lo:[1,0,0] neg_hi:[1,0,0]
	v_lshlrev_b32_e32 v170, 16, v124
	v_and_b32_e32 v171, 0xffff0000, v124
	v_pk_mul_f32 v[170:171], v[168:169], v[170:171]
	v_pk_mul_f32 v[168:169], v[100:101], v[168:169]
	v_cvt_pk_bf16_f32 v105, v170, v171
	v_cvt_pk_bf16_f32 v102, v102, v103
	s_nop 0
	v_max_f32_e32 v169, 0x554ad2e, v169
	v_max_f32_e32 v168, 0x554ad2e, v168
	v_rcp_f32_e32 v170, v168
	v_rcp_f32_e32 v171, v169
	s_nop 0
	v_pk_fma_f32 v[100:101], v[100:101], v[170:171], v[170:171] neg_lo:[1,0,0] neg_hi:[1,0,0]
	v_lshlrev_b32_e32 v170, 16, v129
	v_and_b32_e32 v171, 0xffff0000, v129
	v_pk_mul_f32 v[170:171], v[168:169], v[170:171]
	v_pk_mul_f32 v[168:169], v[98:99], v[168:169]
	v_cvt_pk_bf16_f32 v103, v170, v171
	v_cvt_pk_bf16_f32 v100, v100, v101
	v_add_u32_e32 v101, 0x4400, v172
	v_max_f32_e32 v169, 0x554ad2e, v169
	v_max_f32_e32 v168, 0x554ad2e, v168
	v_rcp_f32_e32 v170, v168
	v_rcp_f32_e32 v171, v169
	ds_write2_b32 v101, v102, v100 offset1:68
	ds_write2_b32 v172, v105, v103 offset1:68
	v_pk_fma_f32 v[98:99], v[98:99], v[170:171], v[170:171] neg_lo:[1,0,0] neg_hi:[1,0,0]
	v_lshlrev_b32_e32 v170, 16, v150
	v_and_b32_e32 v171, 0xffff0000, v150
	v_pk_mul_f32 v[170:171], v[168:169], v[170:171]
	v_pk_mul_f32 v[168:169], v[96:97], v[168:169]
	v_cvt_pk_bf16_f32 v101, v170, v171
	v_cvt_pk_bf16_f32 v98, v98, v99
	ds_write_b32 v172, v101 offset:544
	v_max_f32_e32 v169, 0x554ad2e, v169
	v_max_f32_e32 v168, 0x554ad2e, v168
	v_rcp_f32_e32 v170, v168
	v_rcp_f32_e32 v171, v169
	v_add_u32_e32 v101, 0x200, v133
	ds_write_b32 v172, v98 offset:17952
	v_pk_fma_f32 v[96:97], v[96:97], v[170:171], v[170:171] neg_lo:[1,0,0] neg_hi:[1,0,0]
	v_lshlrev_b32_e32 v170, 16, v153
	v_and_b32_e32 v171, 0xffff0000, v153
	v_pk_mul_f32 v[170:171], v[168:169], v[170:171]
	v_pk_mul_f32 v[168:169], v[94:95], v[168:169]
	v_cvt_pk_bf16_f32 v99, v170, v171
	v_cvt_pk_bf16_f32 v96, v96, v97
	s_nop 0
	v_max_f32_e32 v169, 0x554ad2e, v169
	v_max_f32_e32 v168, 0x554ad2e, v168
	v_rcp_f32_e32 v170, v168
	v_rcp_f32_e32 v171, v169
	s_nop 0
	v_pk_fma_f32 v[94:95], v[94:95], v[170:171], v[170:171] neg_lo:[1,0,0] neg_hi:[1,0,0]
	v_lshlrev_b32_e32 v170, 16, v157
	v_and_b32_e32 v171, 0xffff0000, v157
	v_pk_mul_f32 v[170:171], v[168:169], v[170:171]
	v_pk_mul_f32 v[168:169], v[92:93], v[168:169]
	v_cvt_pk_bf16_f32 v97, v170, v171
	v_cvt_pk_bf16_f32 v94, v94, v95
	v_add_u32_e32 v95, 0x4600, v133
	v_max_f32_e32 v169, 0x554ad2e, v169
	v_max_f32_e32 v168, 0x554ad2e, v168
	v_rcp_f32_e32 v170, v168
	v_rcp_f32_e32 v171, v169
	ds_write2_b32 v95, v96, v94 offset0:76 offset1:144
	ds_write2_b32 v101, v99, v97 offset0:76 offset1:144
	v_add_u32_e32 v97, 0x400, v133
	v_pk_fma_f32 v[92:93], v[92:93], v[170:171], v[170:171] neg_lo:[1,0,0] neg_hi:[1,0,0]
	v_lshlrev_b32_e32 v170, 16, v160
	v_and_b32_e32 v171, 0xffff0000, v160
	v_pk_mul_f32 v[170:171], v[168:169], v[170:171]
	v_pk_mul_f32 v[168:169], v[90:91], v[168:169]
	v_cvt_pk_bf16_f32 v95, v170, v171
	v_cvt_pk_bf16_f32 v92, v92, v93
	s_nop 0
	v_max_f32_e32 v169, 0x554ad2e, v169
	v_max_f32_e32 v168, 0x554ad2e, v168
	v_rcp_f32_e32 v170, v168
	v_rcp_f32_e32 v171, v169
	s_nop 0
	v_pk_fma_f32 v[90:91], v[90:91], v[170:171], v[170:171] neg_lo:[1,0,0] neg_hi:[1,0,0]
	v_lshlrev_b32_e32 v170, 16, v163
	v_and_b32_e32 v171, 0xffff0000, v163
	v_cvt_pk_bf16_f32 v90, v90, v91
	v_add_u32_e32 v91, 0x4800, v133
	v_pk_mul_f32 v[168:169], v[168:169], v[170:171]
	ds_write2_b32 v91, v92, v90 offset0:84 offset1:152
	v_cvt_pk_bf16_f32 v93, v168, v169
	ds_write2_b32 v97, v95, v93 offset0:84 offset1:152
	s_cbranch_vccnz .LBB0_177
; #define LAS __attribute__((address_space(3)))
; __device__ __forceinline__ float exp2_(float x) { return __builtin_amdgcn_exp2f(x); }
; template <int DK, bool IS_A, int NDV>
; __device__ __forceinline__ void mix_stream(const Params& p, LAS unsigned char* lds, int l, int rs, int T, int h, int dir, int dvh) {
;     ...
;                 if (sg == 0) { *(LAS f32x2*)(cdec + 2 * cp) = (f32x2){exp2_(fmaxf(tot0, -115.f)), exp2_(fmaxf(tot1, -115.f))};
;                                *(LAS f32x2*)(csc + 2 * cp) = (f32x2){exp2_(fmaxf(tot0 - ref0, -115.f)), exp2_(fmaxf(tot1 - ref1, -115.f))}; }
	v_add_f32_e32 v1, v166, v1
	v_add_f32_e32 v0, v167, v0
	v_add_f32_e32 v1, v1, v3
	v_add_f32_e32 v0, v0, v2
	v_add_f32_e32 v1, v1, v5
	v_add_f32_e32 v0, v0, v4
	v_add_f32_e32 v3, v1, v7
	v_add_f32_e32 v2, v0, v6
	v_max_f32_e32 v0, 0xc2e60000, v2
	v_max_f32_e32 v1, 0xc2e60000, v3
	v_sub_f32_e32 v2, v2, v167
	v_sub_f32_e32 v3, v3, v166
	v_exp_f32_e32 v0, v0
	v_exp_f32_e32 v1, v1
	v_max_f32_e32 v2, 0xc2e60000, v2
	v_max_f32_e32 v3, 0xc2e60000, v3
	v_exp_f32_e32 v2, v2
	v_exp_f32_e32 v3, v3
	ds_write_b64 v109, v[0:1]
	ds_write_b64 v110, v[2:3]
